# pipelined attention v4 plus s_setprio 1 during the softmax block
# speedup vs baseline: 1.0218x; 1.0218x over previous
; DI void attn_s(const unsigned char* sK, int tt, int qb, int qs, int sub, int l31, int h,
;                const bf16x8 (&qf)[4], f32x16 (&O)[4], float& m, float& l, bf16x8 (&pb)[4]) {
;     ...
;     } else if (tt >= 2 * qb + 1) {
;         const int kbase = (tt - 1) * 64 + 4 * h;
; #pragma unroll
;         for (int k2 = 0; k2 < 2; ++k2)
; #pragma unroll
;             for (int i = 0; i < 16; ++i) {
;                 const int key = kbase + k2 * 32 + (i & 3) + 8 * (i >> 2);
;                 if (key > qs) st[k2][i] = -INFINITY;
;             }
;     }
.Lpipe_loop:
	s_setprio 1
	v_add3_u32 v191, s98, v156, v98
	ds_read_b128 v[172:175], v191 offset:17408
	ds_read_b128 v[176:179], v191 offset:22016
	ds_read_b128 v[180:183], v191 offset:26624
	ds_read_b128 v[192:195], v191 offset:31232
	ds_read_b128 v[200:203], v191 offset:17440
	ds_read_b128 v[204:207], v191 offset:22048
	ds_read_b128 v[208:211], v191 offset:26656
	ds_read_b128 v[212:215], v191 offset:31264
	s_add_i32 s14, s12, 0x41
	s_cmp_le_i32 s14, s0
	s_cbranch_scc1 .Lpipe_nomask_l
	v_subrev_u32_e32 v159, 59, v158
	v_cmp_gt_i32_e32 vcc, v159, v138
	s_nop 1
	v_cndmask_b32_e32 v160, v82, v188, vcc
	v_cmp_lt_i32_e32 vcc, v159, v138
	v_subrev_u32_e32 v159, 57, v158
	s_nop 0
	v_cndmask_b32_e32 v82, v160, v82, vcc
	v_cndmask_b32_e32 v83, v188, v83, vcc
	v_cmp_le_i32_e32 vcc, v159, v138
	v_subrev_u32_e32 v159, 56, v158
	s_nop 0
	v_cndmask_b32_e32 v84, v188, v84, vcc
	v_cmp_le_i32_e32 vcc, v159, v138
	v_subrev_u32_e32 v159, 51, v158
	s_nop 0
	v_cndmask_b32_e32 v85, v188, v85, vcc
	v_cmp_le_i32_e32 vcc, v159, v138
	v_subrev_u32_e32 v159, 50, v158
	s_nop 0
	v_cndmask_b32_e32 v86, v188, v86, vcc
	v_cmp_le_i32_e32 vcc, v159, v138
	v_subrev_u32_e32 v159, 49, v158
	s_nop 0
	v_cndmask_b32_e32 v87, v188, v87, vcc
	v_cmp_le_i32_e32 vcc, v159, v138
	v_subrev_u32_e32 v159, 48, v158
	s_nop 0
	v_cndmask_b32_e32 v88, v188, v88, vcc
	v_cmp_le_i32_e32 vcc, v159, v138
	v_subrev_u32_e32 v159, 43, v158
	s_nop 0
	v_cndmask_b32_e32 v89, v188, v89, vcc
	v_cmp_le_i32_e32 vcc, v159, v138
	v_subrev_u32_e32 v159, 42, v158
	s_nop 0
	v_cndmask_b32_e32 v90, v188, v90, vcc
	v_cmp_le_i32_e32 vcc, v159, v138
	v_subrev_u32_e32 v159, 41, v158
	s_nop 0
	v_cndmask_b32_e32 v91, v188, v91, vcc
	v_cmp_le_i32_e32 vcc, v159, v138
	v_subrev_u32_e32 v159, 40, v158
	s_nop 0
	v_cndmask_b32_e32 v92, v188, v92, vcc
	v_cmp_le_i32_e32 vcc, v159, v138
	v_subrev_u32_e32 v159, 35, v158
	s_nop 0
	v_cndmask_b32_e32 v93, v188, v93, vcc
	v_cmp_le_i32_e32 vcc, v159, v138
	v_subrev_u32_e32 v159, 34, v158
	s_nop 0
	v_cndmask_b32_e32 v94, v188, v94, vcc
	v_cmp_le_i32_e32 vcc, v159, v138
	v_subrev_u32_e32 v159, 33, v158
	s_nop 0
	v_cndmask_b32_e32 v95, v188, v95, vcc
	v_cmp_le_i32_e32 vcc, v159, v138
	v_subrev_u32_e32 v159, 32, v158
	s_nop 0
	v_cndmask_b32_e32 v96, v188, v96, vcc
	v_cmp_le_i32_e32 vcc, v159, v138
	v_subrev_u32_e32 v159, 27, v158
	s_nop 0
	v_cndmask_b32_e32 v97, v188, v97, vcc
	v_cmp_le_i32_e32 vcc, v159, v138
	v_subrev_u32_e32 v159, 26, v158
	s_nop 0
	v_cndmask_b32_e32 v66, v188, v66, vcc
	v_cmp_le_i32_e32 vcc, v159, v138
	v_subrev_u32_e32 v159, 25, v158
	s_nop 0
	v_cndmask_b32_e32 v67, v188, v67, vcc
	v_cmp_le_i32_e32 vcc, v159, v138
	v_subrev_u32_e32 v159, 24, v158
	s_nop 0
	v_cndmask_b32_e32 v68, v188, v68, vcc
	v_cmp_le_i32_e32 vcc, v159, v138
	v_subrev_u32_e32 v159, 19, v158
	s_nop 0
	v_cndmask_b32_e32 v69, v188, v69, vcc
	v_cmp_le_i32_e32 vcc, v159, v138
	v_subrev_u32_e32 v159, 18, v158
	s_nop 0
	v_cndmask_b32_e32 v70, v188, v70, vcc
	v_cmp_le_i32_e32 vcc, v159, v138
	v_subrev_u32_e32 v159, 17, v158
	s_nop 0
	v_cndmask_b32_e32 v71, v188, v71, vcc
	v_cmp_le_i32_e32 vcc, v159, v138
	v_add_u32_e32 v159, -16, v158
	s_nop 0
	v_cndmask_b32_e32 v72, v188, v72, vcc
	v_cmp_le_i32_e32 vcc, v159, v138
	v_add_u32_e32 v159, -11, v158
	s_nop 0
	v_cndmask_b32_e32 v73, v188, v73, vcc
	v_cmp_le_i32_e32 vcc, v159, v138
	v_add_u32_e32 v159, -10, v158
	s_nop 0
	v_cndmask_b32_e32 v74, v188, v74, vcc
	v_cmp_le_i32_e32 vcc, v159, v138
	v_add_u32_e32 v159, -9, v158
	s_nop 0
	v_cndmask_b32_e32 v75, v188, v75, vcc
	v_cmp_le_i32_e32 vcc, v159, v138
	v_add_u32_e32 v159, -8, v158
	s_nop 0
	v_cndmask_b32_e32 v76, v188, v76, vcc
	v_cmp_le_i32_e32 vcc, v159, v138
	v_add_u32_e32 v159, -3, v158
	s_nop 0
	v_cndmask_b32_e32 v77, v188, v77, vcc
	v_cmp_le_i32_e32 vcc, v159, v138
	v_add_u32_e32 v159, -2, v158
	s_nop 0
	v_cndmask_b32_e32 v78, v188, v78, vcc
	v_cmp_le_i32_e32 vcc, v159, v138
	v_add_u32_e32 v159, -1, v158
	s_nop 0
	v_cndmask_b32_e32 v79, v188, v79, vcc
	v_cmp_le_i32_e32 vcc, v159, v138
	s_nop 1
	v_cndmask_b32_e32 v80, v188, v80, vcc
	v_cmp_le_i32_e32 vcc, v158, v138
	s_nop 1
	v_cndmask_b32_e32 v81, v188, v81, vcc

; DI unsigned pk2(float a, float b) { f32x2 v = {a, b}; return __builtin_bit_cast(unsigned, __builtin_convertvector(v, bfv2)); }
; DI void attn_s(const unsigned char* sK, int tt, int qb, int qs, int sub, int l31, int h,
;                const bf16x8 (&qf)[4], f32x16 (&O)[4], float& m, float& l, bf16x8 (&pb)[4]) {
;     ...
; #pragma unroll
;     for (int k2 = 0; k2 < 2; ++k2)
; #pragma unroll
;         for (int i = 0; i < 16; ++i) st[k2][i] = __builtin_amdgcn_exp2f(st[k2][i]);
;     {
;         const f32x16 sv = st[0] + st[1];
;         const float ps = (((sv[0] + sv[1]) + (sv[2] + sv[3])) + ((sv[4] + sv[5]) + (sv[6] + sv[7]))) + (((sv[8] + sv[9]) + (sv[10] + sv[11])) + ((sv[12] + sv[13]) + (sv[14] + sv[15])));
;         l += ps;
;     }
; #pragma unroll
;     for (int k4 = 0; k4 < 4; ++k4) {
;         const int k2 = k4 >> 1, o8 = 8 * (k4 & 1);
;         u32x4 pk;
;         pk.x = pk2(st[k2][o8 + 0], st[k2][o8 + 1]); pk.y = pk2(st[k2][o8 + 2], st[k2][o8 + 3]);
;         pk.z = pk2(st[k2][o8 + 4], st[k2][o8 + 5]); pk.w = pk2(st[k2][o8 + 6], st[k2][o8 + 7]);
;         pb[k4] = __builtin_bit_cast(bf16x8, pk);
;     }
.Lpipe_norescale_l:
	v_exp_f32_e32 v82, v82
	v_exp_f32_e32 v83, v83
	v_exp_f32_e32 v84, v84
	v_exp_f32_e32 v85, v85
	v_exp_f32_e32 v86, v86
	v_exp_f32_e32 v87, v87
	v_exp_f32_e32 v88, v88
	v_exp_f32_e32 v89, v89
	v_exp_f32_e32 v90, v90
	v_exp_f32_e32 v91, v91
	v_exp_f32_e32 v92, v92
	v_exp_f32_e32 v93, v93
	v_exp_f32_e32 v94, v94
	v_exp_f32_e32 v95, v95
	v_exp_f32_e32 v96, v96
	v_exp_f32_e32 v97, v97
	v_exp_f32_e32 v66, v66
	v_exp_f32_e32 v67, v67
	v_exp_f32_e32 v68, v68
	v_exp_f32_e32 v69, v69
	v_exp_f32_e32 v70, v70
	v_exp_f32_e32 v71, v71
	v_exp_f32_e32 v72, v72
	v_exp_f32_e32 v73, v73
	v_exp_f32_e32 v74, v74
	v_exp_f32_e32 v75, v75
	v_exp_f32_e32 v76, v76
	v_exp_f32_e32 v77, v77
	v_exp_f32_e32 v78, v78
	v_exp_f32_e32 v79, v79
	v_exp_f32_e32 v80, v80
	v_exp_f32_e32 v81, v81
	v_cvt_pk_bf16_f32 v216, v82, v83
	v_cvt_pk_bf16_f32 v217, v84, v85
	v_cvt_pk_bf16_f32 v218, v86, v87
	v_cvt_pk_bf16_f32 v219, v88, v89
	v_cvt_pk_bf16_f32 v220, v90, v91
	v_cvt_pk_bf16_f32 v221, v92, v93
	v_cvt_pk_bf16_f32 v222, v94, v95
	v_cvt_pk_bf16_f32 v223, v96, v97
	v_cvt_pk_bf16_f32 v224, v66, v67
	v_cvt_pk_bf16_f32 v225, v68, v69
	v_cvt_pk_bf16_f32 v226, v70, v71
	v_cvt_pk_bf16_f32 v227, v72, v73
	v_cvt_pk_bf16_f32 v228, v74, v75
	v_cvt_pk_bf16_f32 v229, v76, v77
	v_cvt_pk_bf16_f32 v230, v78, v79
	v_cvt_pk_bf16_f32 v231, v80, v81
	v_pk_add_f32 v[68:69], v[84:85], v[68:69]
	v_pk_add_f32 v[66:67], v[82:83], v[66:67]
	v_pk_add_f32 v[72:73], v[88:89], v[72:73]
	v_pk_add_f32 v[70:71], v[86:87], v[70:71]
	v_add_f32_e32 v66, v66, v67
	v_add_f32_e32 v67, v68, v69
	v_add_f32_e32 v66, v66, v67
	v_add_f32_e32 v67, v70, v71
	v_add_f32_e32 v68, v72, v73
	v_pk_add_f32 v[76:77], v[92:93], v[76:77]
	v_pk_add_f32 v[74:75], v[90:91], v[74:75]
	v_add_f32_e32 v67, v67, v68
	v_pk_add_f32 v[80:81], v[96:97], v[80:81]
	v_pk_add_f32 v[78:79], v[94:95], v[78:79]
	v_add_f32_e32 v66, v66, v67
	v_add_f32_e32 v67, v74, v75
	v_add_f32_e32 v68, v76, v77
	v_add_f32_e32 v67, v67, v68
	v_add_f32_e32 v68, v78, v79
	v_add_f32_e32 v69, v80, v81
	v_add_f32_e32 v68, v68, v69
	v_add_f32_e32 v67, v67, v68
	v_add_f32_e32 v66, v66, v67
	v_add_f32_e32 v1, v1, v66
	v_add_u32_e32 v158, 64, v158
	s_mov_b32 s13, s7
	s_add_i32 s4, s7, 1
	s_cmp_lg_u32 s7, 2
	s_cselect_b32 s7, s4, 0
	s_add_i32 s12, s12, 1
	s_cmp_eq_u32 s11, s12
	s_setprio 0
	s_cbranch_scc1 .Lpipe_final
	s_barrier
	s_mul_i32 s98, s13, 0x8c00
	v_add3_u32 v185, s98, v155, v154
	ds_read_b128 v[160:163], v185
	ds_read_b128 v[164:167], v185 offset:32
	ds_read_b128 v[168:171], v185 offset:8704
	ds_read_b128 v[196:199], v185 offset:8736
	s_waitcnt lgkmcnt(11)
	v_mfma_f32_32x32x16_bf16 v[50:65], v[172:175], v[216:219], v[50:65]
	s_waitcnt lgkmcnt(10)
	v_mfma_f32_32x32x16_bf16 v[34:49], v[176:179], v[216:219], v[34:49]
	s_waitcnt lgkmcnt(9)
	v_mfma_f32_32x32x16_bf16 v[18:33], v[180:183], v[216:219], v[18:33]
	s_waitcnt lgkmcnt(8)
	v_mfma_f32_32x32x16_bf16 v[2:17], v[192:195], v[216:219], v[2:17]
	ds_read_b128 v[172:175], v185 offset:64
	ds_read_b128 v[176:179], v185 offset:96
	ds_read_b128 v[180:183], v185 offset:8768
	ds_read_b128 v[192:195], v185 offset:8800
	s_waitcnt lgkmcnt(11)
	v_mfma_f32_32x32x16_bf16 v[50:65], v[200:203], v[220:223], v[50:65]
	s_waitcnt lgkmcnt(10)
	v_mfma_f32_32x32x16_bf16 v[34:49], v[204:207], v[220:223], v[34:49]
	s_waitcnt lgkmcnt(9)
	v_mfma_f32_32x32x16_bf16 v[18:33], v[208:211], v[220:223], v[18:33]
	s_waitcnt lgkmcnt(8)
	v_mfma_f32_32x32x16_bf16 v[2:17], v[212:215], v[220:223], v[2:17]
	ds_read_b128 v[200:203], v191 offset:17472
	ds_read_b128 v[204:207], v191 offset:22080
	ds_read_b128 v[208:211], v191 offset:26688
	ds_read_b128 v[212:215], v191 offset:31296
	s_waitcnt lgkmcnt(11)
	v_mfma_f32_32x32x16_bf16 v[82:97], v[160:163], v[100:103], v[240:255]
	s_waitcnt lgkmcnt(9)
	v_mfma_f32_32x32x16_bf16 v[66:81], v[168:171], v[100:103], v[240:255]
	v_mfma_f32_32x32x16_bf16 v[82:97], v[164:167], v[104:107], v[82:97]
	s_waitcnt lgkmcnt(8)
	v_mfma_f32_32x32x16_bf16 v[66:81], v[196:199], v[104:107], v[66:81]
	ds_read_b128 v[160:163], v191 offset:17504
	ds_read_b128 v[164:167], v191 offset:22112
	ds_read_b128 v[168:171], v191 offset:26720
	ds_read_b128 v[196:199], v191 offset:31328
	s_waitcnt lgkmcnt(11)
	v_mfma_f32_32x32x16_bf16 v[82:97], v[172:175], v[108:111], v[82:97]
	s_waitcnt lgkmcnt(9)
	v_mfma_f32_32x32x16_bf16 v[66:81], v[180:183], v[108:111], v[66:81]
	v_mfma_f32_32x32x16_bf16 v[82:97], v[176:179], v[112:115], v[82:97]
	s_waitcnt lgkmcnt(8)
	v_mfma_f32_32x32x16_bf16 v[66:81], v[192:195], v[112:115], v[66:81]
	s_add_i32 s14, s12, 0x42
	s_cmp_ge_i32 s14, s6
	s_cbranch_scc1 .Lpipe_nost_l
	s_mul_i32 s4, s7, 0x8c00
	s_add_i32 s4, s4, 0
	v_add_u32_e32 v184, s4, v140
	v_add_u32_e32 v185, v184, v139
	v_add_u32_e32 v184, v184, v141
	s_waitcnt vmcnt(3)
	ds_write_b128 v185, v[116:119]
	s_waitcnt vmcnt(2)
	ds_write_b128 v184, v[120:123]
	v_add3_u32 v184, s4, v150, v151
	v_add_u32_e32 v185, v184, v152
	v_add_u32_e32 v184, v184, v153
	v_add_u32_e32 v185, 0x4000, v185
	v_add_u32_e32 v184, 0x4000, v184
	s_waitcnt vmcnt(1)
	ds_write2_b64 v185, v[124:125], v[126:127] offset0:128 offset1:130
	s_waitcnt vmcnt(0)
	ds_write2_b64 v184, v[128:129], v[130:131] offset0:128 offset1:130
